# grid barriers after P2 and P5: the early-arriving blocks 248..255 (one per XCD) issue an L2 writeback on arrival, so the XCD leader's release flushes less; on top of v69
# baseline (speedup 1.0000x reference)
; __device__ __forceinline__ unsigned xb_add(unsigned* p, unsigned v) { return __hip_atomic_fetch_add(p, v, __ATOMIC_RELAXED, __HIP_MEMORY_SCOPE_AGENT); }
; __device__ __forceinline__ void xcd_barrier(const XcdBarrier& b) {
;     ...
;     if (threadIdx.x == 0) {
;         unsigned* bar = b.bar;
;         __builtin_amdgcn_s_waitcnt(0);
;         unsigned nloc = b.st[0], nx = b.st[1];
;         if (nloc == 0u) { xcd_barrier_complete(bar, b.x, nloc, nx); b.st[0] = nloc; b.st[1] = nx; }
;         const unsigned old = xb_add(&bar[XB_XSUB(b.x)], 1u);
.LBB0_305:
	s_mov_b64 s[6:7], exec
	s_lshl_b32 s4, s3, 8
	v_mbcnt_lo_u32_b32 v1, s6, 0
	s_add_u32 s4, s18, s4
	v_mbcnt_hi_u32_b32 v1, s7, v1
	s_addc_u32 s5, s19, 0
	v_cmp_eq_u32_e32 vcc, 0, v1
	s_and_saveexec_b64 s[8:9], vcc
	s_cbranch_execz .LBB0_307
	s_bcnt1_i32_b64 s6, s[6:7]
	v_mov_b32_e32 v3, 0x1000
	v_mov_b32_e32 v4, s6
	s_cmp_lt_u32 s2, 0xf8
	s_cbranch_scc1 .Lewb_a
	buffer_wbl2 sc1
.Lewb_a:
	global_atomic_add v3, v3, v4, s[4:5] offset:1024 sc0

; __device__ __forceinline__ unsigned xb_add(unsigned* p, unsigned v) { return __hip_atomic_fetch_add(p, v, __ATOMIC_RELAXED, __HIP_MEMORY_SCOPE_AGENT); }
; __device__ __forceinline__ void xcd_barrier(const XcdBarrier& b) {
;     ...
;     if (threadIdx.x == 0) {
;         unsigned* bar = b.bar;
;         __builtin_amdgcn_s_waitcnt(0);
;         unsigned nloc = b.st[0], nx = b.st[1];
;         if (nloc == 0u) { xcd_barrier_complete(bar, b.x, nloc, nx); b.st[0] = nloc; b.st[1] = nx; }
;         const unsigned old = xb_add(&bar[XB_XSUB(b.x)], 1u);
.LBB0_1276:
	s_mov_b64 s[6:7], exec
	s_lshl_b32 s3, s3, 8
	v_mbcnt_lo_u32_b32 v1, s6, 0
	s_add_u32 s4, s18, s3
	v_mbcnt_hi_u32_b32 v1, s7, v1
	s_addc_u32 s5, s19, 0
	v_cmp_eq_u32_e32 vcc, 0, v1
	s_and_saveexec_b64 s[8:9], vcc
	s_cbranch_execz .LBB0_1278
	s_bcnt1_i32_b64 s3, s[6:7]
	v_mov_b32_e32 v3, 0x1000
	v_mov_b32_e32 v4, s3
	s_cmp_lt_u32 s2, 0xf8
	s_cbranch_scc1 .Lewb_b
	buffer_wbl2 sc1
